# neighbourhood attention masked tiles: relative-position bias loaded unmasked (EXEC save/restore pairs and dead zero-inits removed; same mask still selects -1e30)
# baseline (speedup 1.0000x reference)
.LBB0_351:
	s_add_i32 s92, s9, -2
	v_add_u32_e32 v17, s4, v216
	ds_read_b64_tr_b16 v[184:185], v17 offset:24576
	ds_read_b64_tr_b16 v[186:187], v17 offset:25088
	s_waitcnt lgkmcnt(9)
	v_mfma_f32_32x32x16_bf16 v[128:143], v[180:183], v[176:179], v[64:79]
	v_add_f32_e32 v2, v96, v97
	v_cvt_pk_bf16_f32 v160, v96, v97
	v_add_f32_e32 v2, v98, v2
	v_cvt_pk_bf16_f32 v161, v98, v99
	v_add_f32_e32 v2, v99, v2
	v_add_f32_e32 v2, v100, v2
	v_add_f32_e32 v2, v101, v2
	ds_read_b64_tr_b16 v[180:181], v17 offset:28672
	ds_read_b64_tr_b16 v[182:183], v17 offset:29184
	s_waitcnt lgkmcnt(10)
	v_mfma_f32_32x32x16_bf16 v[112:127], v[156:159], v[176:179], v[64:79]
	v_add_f32_e32 v2, v102, v2
	v_cvt_pk_bf16_f32 v162, v100, v101
	v_add_f32_e32 v2, v103, v2
	v_cvt_pk_bf16_f32 v163, v102, v103
	v_add_f32_e32 v2, v104, v2
	v_add_f32_e32 v2, v105, v2
	ds_read_b64_tr_b16 v[96:97], v17 offset:25600
	ds_read_b64_tr_b16 v[98:99], v17 offset:26112
	s_waitcnt lgkmcnt(11)
	v_mfma_f32_32x32x16_bf16 v[128:143], v[152:155], v[172:175], v[128:143]
	v_add_f32_e32 v2, v106, v2
	v_cvt_pk_bf16_f32 v10, v104, v105
	v_add_f32_e32 v2, v107, v2
	v_cvt_pk_bf16_f32 v11, v106, v107
	v_add_f32_e32 v2, v108, v2
	v_add_f32_e32 v2, v109, v2
	ds_read_b64_tr_b16 v[100:101], v17 offset:29696
	ds_read_b64_tr_b16 v[102:103], v17 offset:30208
	s_waitcnt lgkmcnt(12)
	v_mfma_f32_32x32x16_bf16 v[112:127], v[148:151], v[172:175], v[112:127]
	v_add_f32_e32 v2, v110, v2
	v_cvt_pk_bf16_f32 v12, v108, v109
	v_add_f32_e32 v2, v111, v2
	v_cvt_pk_bf16_f32 v13, v110, v111
	v_add_f32_e32 v2, v80, v2
	v_add_f32_e32 v2, v81, v2
	ds_read_b64_tr_b16 v[104:105], v17 offset:26624
	ds_read_b64_tr_b16 v[106:107], v17 offset:27136
	s_waitcnt lgkmcnt(13)
	v_mfma_f32_32x32x16_bf16 v[128:143], v[144:147], v[168:171], v[128:143]
	v_add_f32_e32 v2, v82, v2
	v_cvt_pk_bf16_f32 v6, v80, v81
	v_add_f32_e32 v2, v83, v2
	v_cvt_pk_bf16_f32 v7, v82, v83
	v_add_f32_e32 v2, v84, v2
	v_add_f32_e32 v2, v85, v2
	ds_read_b64_tr_b16 v[80:81], v17 offset:30720
	ds_read_b64_tr_b16 v[82:83], v17 offset:31232
	s_waitcnt lgkmcnt(14)
	v_mfma_f32_32x32x16_bf16 v[112:127], v[26:29], v[168:171], v[112:127]
	v_add_f32_e32 v2, v86, v2
	v_cvt_pk_bf16_f32 v8, v84, v85
	v_add_f32_e32 v2, v87, v2
	v_cvt_pk_bf16_f32 v9, v86, v87
	v_add_f32_e32 v2, v88, v2
	v_add_f32_e32 v2, v89, v2
	ds_read_b64_tr_b16 v[84:85], v17 offset:27648
	ds_read_b64_tr_b16 v[86:87], v17 offset:28160
	s_waitcnt lgkmcnt(14)
	v_mfma_f32_32x32x16_bf16 v[128:143], v[22:25], v[164:167], v[128:143]
	v_add_f32_e32 v2, v90, v2
	v_cvt_pk_bf16_f32 v3, v90, v91
	v_add_f32_e32 v2, v91, v2
	v_add_f32_e32 v2, v92, v2
	v_add_f32_e32 v22, v93, v2
	v_cvt_pk_bf16_f32 v2, v88, v89
	ds_read_b64_tr_b16 v[88:89], v17 offset:31744
	ds_read_b64_tr_b16 v[90:91], v17 offset:32256
	v_mfma_f32_32x32x16_bf16 v[112:127], v[18:21], v[164:167], v[112:127]
	v_add_f32_e32 v4, v94, v22
	v_cvt_pk_bf16_f32 v5, v94, v95
	v_add_f32_e32 v4, v95, v4
	v_add_f32_e32 v108, 0, v4
	v_cvt_pk_bf16_f32 v4, v92, v93
	s_add_i32 s6, s9, -1
	s_add_i32 s4, s93, s33
	s_add_i32 s7, s6, s8
	s_cmp_gt_u32 s92, 2
	s_cselect_b64 s[10:11], -1, 0
	s_mov_b32 s5, m0
	s_mov_b32 m0, s4
	s_nop 0
	global_load_lds_dwordx4 v[190:191], off
	s_mov_b32 m0, s5
	s_and_b64 s[4:5], s[10:11], exec
	s_cselect_b32 s82, s7, s6
	s_lshl_b64 s[4:5], s[82:83], 13
	v_lshl_add_u64 v[18:19], v[14:15], 0, s[4:5]
	s_add_i32 s4, s91, s88
	s_mov_b32 s5, m0
	s_mov_b32 m0, s4
	s_nop 0
	global_load_lds_dwordx4 v[18:19], off
	s_mov_b32 m0, s5
	s_cmp_lt_u32 s92, 4
	s_cbranch_scc1 .LBB0_419
	s_add_i32 s4, s90, s9
	s_add_i32 s4, s4, -6
	s_cmp_gt_u32 s4, 7
	s_cbranch_scc1 .LBB0_418
	ds_read_b32 v18, v193
	ds_read_b32 v17, v193 offset:128
	ds_read_b32 v20, v193 offset:4
	ds_read_b32 v19, v193 offset:132
	ds_read_b32 v22, v193 offset:8
	ds_read_b32 v21, v193 offset:136
	ds_read_b32 v24, v193 offset:12
	ds_read_b32 v23, v193 offset:140
	ds_read_b32 v26, v193 offset:32
	ds_read_b32 v25, v193 offset:160
	ds_read_b32 v28, v193 offset:36
	ds_read_b32 v27, v193 offset:164
	ds_read_b32 v30, v193 offset:40
	ds_read_b32 v29, v193 offset:168
	ds_read_b32 v92, v193 offset:44
	ds_read_b32 v31, v193 offset:172
	ds_read_b32 v94, v193 offset:64
	ds_read_b32 v93, v193 offset:192
	ds_read_b32 v109, v193 offset:68
	ds_read_b32 v95, v193 offset:196
	ds_read_b32 v111, v193 offset:72
	ds_read_b32 v110, v193 offset:200
	ds_read_b32 v145, v193 offset:76
	ds_read_b32 v144, v193 offset:204
	ds_read_b32 v147, v193 offset:96
	ds_read_b32 v146, v193 offset:224
	ds_read_b32 v149, v193 offset:100
	ds_read_b32 v148, v193 offset:228
	ds_read_b32 v151, v193 offset:104
	ds_read_b32 v150, v193 offset:232
	ds_read_b32 v153, v193 offset:108
	ds_read_b32 v152, v193 offset:236
	s_waitcnt lgkmcnt(0)
	v_add_f32_e32 v17, v112, v17
	v_cndmask_b32_e64 v112, v16, v17, s[14:15]
	v_add_f32_e32 v17, v129, v20
	v_cndmask_b32_e64 v129, v16, v17, s[16:17]
	v_add_f32_e32 v17, v113, v19
	v_cndmask_b32_e64 v113, v16, v17, s[18:19]
	v_add_f32_e32 v17, v130, v22
	v_cndmask_b32_e64 v130, v16, v17, s[20:21]
	v_add_f32_e32 v17, v114, v21
	v_cndmask_b32_e64 v114, v16, v17, s[22:23]
	v_add_f32_e32 v17, v131, v24
	v_cndmask_b32_e64 v131, v16, v17, s[24:25]
	v_add_f32_e32 v17, v115, v23
	v_cndmask_b32_e64 v115, v16, v17, s[26:27]
	v_add_f32_e32 v17, v132, v26
	v_cndmask_b32_e64 v132, v16, v17, s[28:29]
	v_add_f32_e32 v17, v116, v25
	v_cndmask_b32_e64 v116, v16, v17, s[30:31]
	v_add_f32_e32 v17, v133, v28
	v_cndmask_b32_e64 v133, v16, v17, s[34:35]
	v_add_f32_e32 v17, v117, v27
	v_cndmask_b32_e64 v117, v16, v17, s[36:37]
	v_add_f32_e32 v17, v134, v30
	v_cndmask_b32_e64 v134, v16, v17, s[38:39]
	v_add_f32_e32 v17, v118, v29
	v_cndmask_b32_e64 v118, v16, v17, s[40:41]
	v_add_f32_e32 v17, v135, v92
	v_cndmask_b32_e64 v135, v16, v17, s[42:43]
	v_add_f32_e32 v17, v119, v31
	v_cndmask_b32_e64 v119, v16, v17, s[44:45]
	v_add_f32_e32 v17, v136, v94
	v_cndmask_b32_e64 v136, v16, v17, s[46:47]
	v_add_f32_e32 v17, v120, v93
	v_cndmask_b32_e64 v120, v16, v17, s[48:49]
	v_add_f32_e32 v17, v137, v109
	v_cndmask_b32_e64 v137, v16, v17, s[50:51]
	v_add_f32_e32 v17, v121, v95
	v_cndmask_b32_e64 v121, v16, v17, s[52:53]
	v_add_f32_e32 v17, v138, v111
	v_cndmask_b32_e64 v138, v16, v17, s[54:55]
	v_add_f32_e32 v17, v122, v110
	v_cndmask_b32_e64 v122, v16, v17, s[56:57]
	v_add_f32_e32 v17, v139, v145
	v_cndmask_b32_e64 v139, v16, v17, s[58:59]
	v_add_f32_e32 v17, v123, v144
	v_cndmask_b32_e64 v123, v16, v17, s[60:61]
	v_add_f32_e32 v17, v140, v147
	v_cndmask_b32_e64 v140, v16, v17, s[62:63]
	v_add_f32_e32 v17, v124, v146
	v_cndmask_b32_e64 v124, v16, v17, s[64:65]
	v_add_f32_e32 v17, v141, v149
	v_cndmask_b32_e64 v141, v16, v17, s[66:67]
	v_add_f32_e32 v17, v125, v148
	v_cndmask_b32_e64 v125, v16, v17, s[68:69]
	v_add_f32_e32 v17, v142, v151
	v_cndmask_b32_e64 v142, v16, v17, s[70:71]
	v_add_f32_e32 v17, v126, v150
	v_cndmask_b32_e64 v126, v16, v17, s[72:73]
	v_add_f32_e32 v17, v143, v153
	v_add_f32_e32 v18, v128, v18
	v_cndmask_b32_e64 v143, v16, v17, s[74:75]
	v_add_f32_e32 v17, v127, v152
	v_cndmask_b32_e64 v128, v16, v18, s[12:13]
	v_cndmask_b32_e64 v127, v16, v17, s[76:77]
	s_branch .LBB0_419

.LBB0_422:
	s_add_i32 s4, s91, 0x2000
	s_cmpk_lg_i32 s91, 0x4000
	s_cselect_b32 s94, s4, 0
	v_add_u32_e32 v17, s93, v216
	ds_read_b64_tr_b16 v[148:149], v17 offset:24576
	ds_read_b64_tr_b16 v[150:151], v17 offset:25088
	s_waitcnt lgkmcnt(9)
	v_mfma_f32_32x32x16_bf16 v[96:111], v[92:95], v[176:179], v[64:79]
	v_add_f32_e32 v2, v128, v129
	v_cvt_pk_bf16_f32 v160, v128, v129
	v_add_f32_e32 v2, v130, v2
	v_cvt_pk_bf16_f32 v161, v130, v131
	v_add_f32_e32 v2, v131, v2
	v_add_f32_e32 v2, v132, v2
	v_add_f32_e32 v2, v133, v2
	ds_read_b64_tr_b16 v[144:145], v17 offset:28672
	ds_read_b64_tr_b16 v[146:147], v17 offset:29184
	s_waitcnt lgkmcnt(10)
	v_mfma_f32_32x32x16_bf16 v[80:95], v[180:183], v[176:179], v[64:79]
	v_add_f32_e32 v2, v134, v2
	v_cvt_pk_bf16_f32 v162, v132, v133
	v_add_f32_e32 v2, v135, v2
	v_cvt_pk_bf16_f32 v163, v134, v135
	v_add_f32_e32 v2, v136, v2
	v_add_f32_e32 v2, v137, v2
	ds_read_b64_tr_b16 v[128:129], v17 offset:25600
	ds_read_b64_tr_b16 v[130:131], v17 offset:26112
	s_waitcnt lgkmcnt(11)
	v_mfma_f32_32x32x16_bf16 v[96:111], v[184:187], v[172:175], v[96:111]
	v_add_f32_e32 v2, v138, v2
	v_cvt_pk_bf16_f32 v10, v136, v137
	v_add_f32_e32 v2, v139, v2
	v_cvt_pk_bf16_f32 v11, v138, v139
	v_add_f32_e32 v2, v140, v2
	v_add_f32_e32 v2, v141, v2
	ds_read_b64_tr_b16 v[132:133], v17 offset:29696
	ds_read_b64_tr_b16 v[134:135], v17 offset:30208
	s_waitcnt lgkmcnt(12)
	v_mfma_f32_32x32x16_bf16 v[80:95], v[156:159], v[172:175], v[80:95]
	v_add_f32_e32 v2, v142, v2
	v_cvt_pk_bf16_f32 v12, v140, v141
	v_add_f32_e32 v2, v143, v2
	v_cvt_pk_bf16_f32 v13, v142, v143
	v_add_f32_e32 v2, v112, v2
	v_add_f32_e32 v2, v113, v2
	ds_read_b64_tr_b16 v[136:137], v17 offset:26624
	ds_read_b64_tr_b16 v[138:139], v17 offset:27136
	s_waitcnt lgkmcnt(13)
	v_mfma_f32_32x32x16_bf16 v[96:111], v[152:155], v[168:171], v[96:111]
	v_add_f32_e32 v2, v114, v2
	v_cvt_pk_bf16_f32 v6, v112, v113
	v_add_f32_e32 v2, v115, v2
	v_cvt_pk_bf16_f32 v7, v114, v115
	v_add_f32_e32 v2, v116, v2
	v_add_f32_e32 v2, v117, v2
	ds_read_b64_tr_b16 v[112:113], v17 offset:30720
	ds_read_b64_tr_b16 v[114:115], v17 offset:31232
	s_waitcnt lgkmcnt(14)
	v_mfma_f32_32x32x16_bf16 v[80:95], v[26:29], v[168:171], v[80:95]
	v_add_f32_e32 v2, v118, v2
	v_cvt_pk_bf16_f32 v8, v116, v117
	v_add_f32_e32 v2, v119, v2
	v_cvt_pk_bf16_f32 v9, v118, v119
	v_add_f32_e32 v2, v120, v2
	v_add_f32_e32 v2, v121, v2
	ds_read_b64_tr_b16 v[116:117], v17 offset:27648
	ds_read_b64_tr_b16 v[118:119], v17 offset:28160
	s_waitcnt lgkmcnt(14)
	v_mfma_f32_32x32x16_bf16 v[96:111], v[22:25], v[164:167], v[96:111]
	v_add_f32_e32 v2, v122, v2
	v_cvt_pk_bf16_f32 v3, v122, v123
	v_add_f32_e32 v2, v123, v2
	v_add_f32_e32 v2, v124, v2
	v_add_f32_e32 v22, v125, v2
	v_cvt_pk_bf16_f32 v2, v120, v121
	ds_read_b64_tr_b16 v[120:121], v17 offset:31744
	ds_read_b64_tr_b16 v[122:123], v17 offset:32256
	v_mfma_f32_32x32x16_bf16 v[80:95], v[18:21], v[164:167], v[80:95]
	v_add_f32_e32 v4, v126, v22
	v_cvt_pk_bf16_f32 v5, v126, v127
	v_add_f32_e32 v4, v127, v4
	v_add_f32_e32 v140, 0, v4
	v_cvt_pk_bf16_f32 v4, v124, v125
	s_add_i32 s4, s91, s33
	v_lshl_add_u64 v[18:19], v[190:191], 0, s[86:87]
	s_mov_b32 s5, m0
	s_mov_b32 m0, s4
	s_nop 0
	global_load_lds_dwordx4 v[18:19], off
	s_mov_b32 m0, s5
	s_cmp_gt_u32 s92, 1
	v_readlane_b32 s4, v255, 11
	s_cselect_b32 s4, s4, 0
	s_add_i32 s82, s4, s9
	s_lshl_b64 s[4:5], s[82:83], 13
	v_lshl_add_u64 v[18:19], v[14:15], 0, s[4:5]
	s_add_i32 s4, s94, s88
	s_mov_b32 s5, m0
	s_mov_b32 m0, s4
	s_nop 0
	global_load_lds_dwordx4 v[18:19], off
	s_mov_b32 m0, s5
	s_andn2_b64 vcc, exec, s[10:11]
	s_cbranch_vccnz .LBB0_490
	s_add_i32 s4, s90, s9
	s_add_i32 s4, s4, -5
	s_cmp_gt_u32 s4, 7
	s_cbranch_scc1 .LBB0_489
	ds_read_b32 v18, v193 offset:124
	ds_read_b32 v17, v193 offset:252
	ds_read_b32 v20, v193 offset:128
	ds_read_b32 v19, v193 offset:256
	ds_read_b32 v22, v193 offset:132
	ds_read_b32 v21, v193 offset:260
	ds_read_b32 v24, v193 offset:136
	ds_read_b32 v23, v193 offset:264
	ds_read_b32 v26, v193 offset:156
	ds_read_b32 v25, v193 offset:284
	ds_read_b32 v28, v193 offset:160
	ds_read_b32 v27, v193 offset:288
	ds_read_b32 v30, v193 offset:164
	ds_read_b32 v29, v193 offset:292
	ds_read_b32 v124, v193 offset:168
	ds_read_b32 v31, v193 offset:296
	ds_read_b32 v126, v193 offset:188
	ds_read_b32 v125, v193 offset:316
	ds_read_b32 v141, v193 offset:192
	ds_read_b32 v127, v193 offset:320
	ds_read_b32 v143, v193 offset:196
	ds_read_b32 v142, v193 offset:324
	ds_read_b32 v153, v193 offset:200
	ds_read_b32 v152, v193 offset:328
	ds_read_b32 v155, v193 offset:220
	ds_read_b32 v154, v193 offset:348
	ds_read_b32 v157, v193 offset:224
	ds_read_b32 v156, v193 offset:352
	ds_read_b32 v159, v193 offset:228
	ds_read_b32 v158, v193 offset:356
	ds_read_b32 v181, v193 offset:232
	ds_read_b32 v180, v193 offset:360
	s_waitcnt lgkmcnt(0)
	v_add_f32_e32 v17, v80, v17
	v_cndmask_b32_e64 v80, v16, v17, s[14:15]
	v_add_f32_e32 v17, v97, v20
	v_cndmask_b32_e64 v97, v16, v17, s[16:17]
	v_add_f32_e32 v17, v81, v19
	v_cndmask_b32_e64 v81, v16, v17, s[18:19]
	v_add_f32_e32 v17, v98, v22
	v_cndmask_b32_e64 v98, v16, v17, s[20:21]
	v_add_f32_e32 v17, v82, v21
	v_cndmask_b32_e64 v82, v16, v17, s[22:23]
	v_add_f32_e32 v17, v99, v24
	v_cndmask_b32_e64 v99, v16, v17, s[24:25]
	v_add_f32_e32 v17, v83, v23
	v_cndmask_b32_e64 v83, v16, v17, s[26:27]
	v_add_f32_e32 v17, v100, v26
	v_cndmask_b32_e64 v100, v16, v17, s[28:29]
	v_add_f32_e32 v17, v84, v25
	v_cndmask_b32_e64 v84, v16, v17, s[30:31]
	v_add_f32_e32 v17, v101, v28
	v_cndmask_b32_e64 v101, v16, v17, s[34:35]
	v_add_f32_e32 v17, v85, v27
	v_cndmask_b32_e64 v85, v16, v17, s[36:37]
	v_add_f32_e32 v17, v102, v30
	v_cndmask_b32_e64 v102, v16, v17, s[38:39]
	v_add_f32_e32 v17, v86, v29
	v_cndmask_b32_e64 v86, v16, v17, s[40:41]
	v_add_f32_e32 v17, v103, v124
	v_cndmask_b32_e64 v103, v16, v17, s[42:43]
	v_add_f32_e32 v17, v87, v31
	v_cndmask_b32_e64 v87, v16, v17, s[44:45]
	v_add_f32_e32 v17, v104, v126
	v_cndmask_b32_e64 v104, v16, v17, s[46:47]
	v_add_f32_e32 v17, v88, v125
	v_cndmask_b32_e64 v88, v16, v17, s[48:49]
	v_add_f32_e32 v17, v105, v141
	v_cndmask_b32_e64 v105, v16, v17, s[50:51]
	v_add_f32_e32 v17, v89, v127
	v_cndmask_b32_e64 v89, v16, v17, s[52:53]
	v_add_f32_e32 v17, v106, v143
	v_cndmask_b32_e64 v106, v16, v17, s[54:55]
	v_add_f32_e32 v17, v90, v142
	v_cndmask_b32_e64 v90, v16, v17, s[56:57]
	v_add_f32_e32 v17, v107, v153
	v_cndmask_b32_e64 v107, v16, v17, s[58:59]
	v_add_f32_e32 v17, v91, v152
	v_cndmask_b32_e64 v91, v16, v17, s[60:61]
	v_add_f32_e32 v17, v108, v155
	v_cndmask_b32_e64 v108, v16, v17, s[62:63]
	v_add_f32_e32 v17, v92, v154
	v_cndmask_b32_e64 v92, v16, v17, s[64:65]
	v_add_f32_e32 v17, v109, v157
	v_cndmask_b32_e64 v109, v16, v17, s[66:67]
	v_add_f32_e32 v17, v93, v156
	v_cndmask_b32_e64 v93, v16, v17, s[68:69]
	v_add_f32_e32 v17, v110, v159
	v_cndmask_b32_e64 v110, v16, v17, s[70:71]
	v_add_f32_e32 v17, v94, v158
	v_cndmask_b32_e64 v94, v16, v17, s[72:73]
	v_add_f32_e32 v17, v111, v181
	v_add_f32_e32 v18, v96, v18
	v_cndmask_b32_e64 v111, v16, v17, s[74:75]
	v_add_f32_e32 v17, v95, v180
	v_cndmask_b32_e64 v96, v16, v18, s[12:13]
	v_cndmask_b32_e64 v95, v16, v17, s[76:77]
	s_branch .LBB0_490

.LBB0_504:
	s_movk_i32 s4, 0xe000
	s_mov_b32 s5, -1
	v_lshl_add_u64 v[18:19], v[14:15], 0, s[4:5]
	s_add_i32 s4, s91, s88
	s_mov_b32 s5, m0
	s_mov_b32 m0, s4
	s_nop 0
	global_load_lds_dwordx4 v[18:19], off
	s_mov_b32 m0, s5
	s_add_i32 s93, s90, s82
	s_add_i32 s4, s93, -4
	s_cmp_gt_u32 s4, 7
	s_cbranch_scc1 .LBB0_570
	ds_read_b32 v18, v0
	ds_read_b32 v17, v0 offset:128
	ds_read_b32 v20, v0 offset:4
	ds_read_b32 v19, v0 offset:132
	ds_read_b32 v22, v0 offset:8
	ds_read_b32 v21, v0 offset:136
	ds_read_b32 v24, v0 offset:12
	ds_read_b32 v23, v0 offset:140
	ds_read_b32 v26, v0 offset:32
	ds_read_b32 v25, v0 offset:160
	ds_read_b32 v28, v0 offset:36
	ds_read_b32 v27, v0 offset:164
	ds_read_b32 v30, v0 offset:40
	ds_read_b32 v29, v0 offset:168
	ds_read_b32 v87, v0 offset:44
	ds_read_b32 v31, v0 offset:172
	ds_read_b32 v89, v0 offset:64
	ds_read_b32 v88, v0 offset:192
	ds_read_b32 v91, v0 offset:68
	ds_read_b32 v90, v0 offset:196
	ds_read_b32 v93, v0 offset:72
	ds_read_b32 v92, v0 offset:200
	ds_read_b32 v95, v0 offset:76
	ds_read_b32 v94, v0 offset:204
	ds_read_b32 v156, v0 offset:96
	ds_read_b32 v157, v0 offset:224
	ds_read_b32 v159, v0 offset:100
	ds_read_b32 v158, v0 offset:228
	ds_read_b32 v221, v0 offset:104
	ds_read_b32 v220, v0 offset:232
	ds_read_b32 v223, v0 offset:108
	ds_read_b32 v222, v0 offset:236
	s_waitcnt lgkmcnt(0)
	v_add_f32_e32 v17, v128, v17
	v_cndmask_b32_e64 v80, v16, v17, s[14:15]
	v_add_f32_e32 v17, v113, v20
	v_cndmask_b32_e64 v145, v16, v17, s[16:17]
	v_add_f32_e32 v17, v129, v19
	v_cndmask_b32_e64 v81, v16, v17, s[18:19]
	v_add_f32_e32 v17, v114, v22
	v_cndmask_b32_e64 v146, v16, v17, s[20:21]
	v_add_f32_e32 v17, v130, v21
	v_cndmask_b32_e64 v82, v16, v17, s[22:23]
	v_add_f32_e32 v17, v115, v24
	v_cndmask_b32_e64 v147, v16, v17, s[24:25]
	v_add_f32_e32 v17, v131, v23
	v_cndmask_b32_e64 v83, v16, v17, s[26:27]
	v_add_f32_e32 v17, v116, v26
	v_cndmask_b32_e64 v148, v16, v17, s[28:29]
	v_add_f32_e32 v17, v132, v25
	v_cndmask_b32_e64 v84, v16, v17, s[30:31]
	v_add_f32_e32 v17, v117, v28
	v_cndmask_b32_e64 v149, v16, v17, s[34:35]
	v_add_f32_e32 v17, v133, v27
	v_cndmask_b32_e64 v85, v16, v17, s[36:37]
	v_add_f32_e32 v17, v118, v30
	v_cndmask_b32_e64 v150, v16, v17, s[38:39]
	v_add_f32_e32 v17, v134, v29
	v_cndmask_b32_e64 v86, v16, v17, s[40:41]
	v_add_f32_e32 v17, v119, v87
	v_cndmask_b32_e64 v151, v16, v17, s[42:43]
	v_add_f32_e32 v17, v135, v31
	v_cndmask_b32_e64 v87, v16, v17, s[44:45]
	v_add_f32_e32 v17, v120, v89
	v_cndmask_b32_e64 v152, v16, v17, s[46:47]
	v_add_f32_e32 v17, v136, v88
	v_cndmask_b32_e64 v88, v16, v17, s[48:49]
	v_add_f32_e32 v17, v121, v91
	v_cndmask_b32_e64 v153, v16, v17, s[50:51]
	v_add_f32_e32 v17, v137, v90
	v_cndmask_b32_e64 v89, v16, v17, s[52:53]
	v_add_f32_e32 v17, v122, v93
	v_cndmask_b32_e64 v154, v16, v17, s[54:55]
	v_add_f32_e32 v17, v138, v92
	v_cndmask_b32_e64 v90, v16, v17, s[56:57]
	v_add_f32_e32 v17, v123, v95
	v_cndmask_b32_e64 v155, v16, v17, s[58:59]
	v_add_f32_e32 v17, v139, v94
	v_cndmask_b32_e64 v91, v16, v17, s[60:61]
	v_add_f32_e32 v17, v124, v156
	v_cndmask_b32_e64 v156, v16, v17, s[62:63]
	v_add_f32_e32 v17, v140, v157
	v_cndmask_b32_e64 v92, v16, v17, s[64:65]
	v_add_f32_e32 v17, v125, v159
	v_cndmask_b32_e64 v157, v16, v17, s[66:67]
	v_add_f32_e32 v17, v141, v158
	v_cndmask_b32_e64 v93, v16, v17, s[68:69]
	v_add_f32_e32 v17, v126, v221
	v_cndmask_b32_e64 v158, v16, v17, s[70:71]
	v_add_f32_e32 v17, v142, v220
	v_cndmask_b32_e64 v94, v16, v17, s[72:73]
	v_add_f32_e32 v17, v127, v223
	v_add_f32_e32 v18, v112, v18
	v_cndmask_b32_e64 v159, v16, v17, s[74:75]
	v_add_f32_e32 v17, v143, v222
	v_cndmask_b32_e64 v144, v16, v18, s[12:13]
	v_cndmask_b32_e64 v95, v16, v17, s[76:77]
	s_branch .LBB0_571

.LBB0_578:
	s_add_i32 s4, s91, 0x2000
	s_cmpk_lg_i32 s91, 0x4000
	s_cselect_b32 s92, s4, 0
	s_add_i32 s4, s92, s88
	s_mov_b32 s5, m0
	s_mov_b32 m0, s4
	s_nop 0
	global_load_lds_dwordx4 v[14:15], off
	s_mov_b32 m0, s5
	s_add_i32 s93, s93, -3
	s_cmp_gt_u32 s93, 7
	s_cbranch_scc1 .LBB0_646
	ds_read_b32 v18, v0 offset:124
	ds_read_b32 v17, v0 offset:252
	ds_read_b32 v20, v0 offset:128
	ds_read_b32 v19, v0 offset:256
	ds_read_b32 v22, v0 offset:132
	ds_read_b32 v21, v0 offset:260
	ds_read_b32 v24, v0 offset:136
	ds_read_b32 v23, v0 offset:264
	ds_read_b32 v26, v0 offset:156
	ds_read_b32 v25, v0 offset:284
	ds_read_b32 v28, v0 offset:160
	ds_read_b32 v27, v0 offset:288
	ds_read_b32 v30, v0 offset:164
	ds_read_b32 v29, v0 offset:292
	ds_read_b32 v87, v0 offset:168
	ds_read_b32 v31, v0 offset:296
	ds_read_b32 v89, v0 offset:188
	ds_read_b32 v88, v0 offset:316
	ds_read_b32 v91, v0 offset:192
	ds_read_b32 v90, v0 offset:320
	ds_read_b32 v93, v0 offset:196
	ds_read_b32 v92, v0 offset:324
	ds_read_b32 v95, v0 offset:200
	ds_read_b32 v94, v0 offset:328
	ds_read_b32 v146, v0 offset:220
	ds_read_b32 v145, v0 offset:348
	ds_read_b32 v148, v0 offset:224
	ds_read_b32 v147, v0 offset:352
	ds_read_b32 v150, v0 offset:228
	ds_read_b32 v149, v0 offset:356
	ds_read_b32 v152, v0 offset:232
	ds_read_b32 v151, v0 offset:360
	s_waitcnt lgkmcnt(0)
	v_add_f32_e32 v17, v112, v17
	v_cndmask_b32_e64 v80, v16, v17, s[14:15]
	v_add_f32_e32 v17, v97, v20
	v_cndmask_b32_e64 v97, v16, v17, s[16:17]
	v_add_f32_e32 v17, v113, v19
	v_cndmask_b32_e64 v81, v16, v17, s[18:19]
	v_add_f32_e32 v17, v98, v22
	v_cndmask_b32_e64 v98, v16, v17, s[20:21]
	v_add_f32_e32 v17, v114, v21
	v_cndmask_b32_e64 v82, v16, v17, s[22:23]
	v_add_f32_e32 v17, v99, v24
	v_cndmask_b32_e64 v99, v16, v17, s[24:25]
	v_add_f32_e32 v17, v115, v23
	v_cndmask_b32_e64 v83, v16, v17, s[26:27]
	v_add_f32_e32 v17, v100, v26
	v_cndmask_b32_e64 v100, v16, v17, s[28:29]
	v_add_f32_e32 v17, v116, v25
	v_cndmask_b32_e64 v84, v16, v17, s[30:31]
	v_add_f32_e32 v17, v101, v28
	v_cndmask_b32_e64 v101, v16, v17, s[34:35]
	v_add_f32_e32 v17, v117, v27
	v_cndmask_b32_e64 v85, v16, v17, s[36:37]
	v_add_f32_e32 v17, v102, v30
	v_cndmask_b32_e64 v102, v16, v17, s[38:39]
	v_add_f32_e32 v17, v118, v29
	v_cndmask_b32_e64 v86, v16, v17, s[40:41]
	v_add_f32_e32 v17, v103, v87
	v_cndmask_b32_e64 v103, v16, v17, s[42:43]
	v_add_f32_e32 v17, v119, v31
	v_cndmask_b32_e64 v87, v16, v17, s[44:45]
	v_add_f32_e32 v17, v104, v89
	v_cndmask_b32_e64 v104, v16, v17, s[46:47]
	v_add_f32_e32 v17, v120, v88
	v_cndmask_b32_e64 v88, v16, v17, s[48:49]
	v_add_f32_e32 v17, v105, v91
	v_cndmask_b32_e64 v105, v16, v17, s[50:51]
	v_add_f32_e32 v17, v121, v90
	v_cndmask_b32_e64 v89, v16, v17, s[52:53]
	v_add_f32_e32 v17, v106, v93
	v_cndmask_b32_e64 v106, v16, v17, s[54:55]
	v_add_f32_e32 v17, v122, v92
	v_cndmask_b32_e64 v90, v16, v17, s[56:57]
	v_add_f32_e32 v17, v107, v95
	v_cndmask_b32_e64 v107, v16, v17, s[58:59]
	v_add_f32_e32 v17, v123, v94
	v_cndmask_b32_e64 v91, v16, v17, s[60:61]
	v_add_f32_e32 v17, v108, v146
	v_cndmask_b32_e64 v108, v16, v17, s[62:63]
	v_add_f32_e32 v17, v124, v145
	v_cndmask_b32_e64 v92, v16, v17, s[64:65]
	v_add_f32_e32 v17, v109, v148
	v_cndmask_b32_e64 v109, v16, v17, s[66:67]
	v_add_f32_e32 v17, v125, v147
	v_cndmask_b32_e64 v93, v16, v17, s[68:69]
	v_add_f32_e32 v17, v110, v150
	v_cndmask_b32_e64 v110, v16, v17, s[70:71]
	v_add_f32_e32 v17, v126, v149
	v_cndmask_b32_e64 v94, v16, v17, s[72:73]
	v_add_f32_e32 v17, v111, v152
	v_add_f32_e32 v18, v96, v18
	v_cndmask_b32_e64 v111, v16, v17, s[74:75]
	v_add_f32_e32 v17, v127, v151
	v_cndmask_b32_e64 v96, v16, v18, s[12:13]
	v_cndmask_b32_e64 v95, v16, v17, s[76:77]
	s_branch .LBB0_647

.LBB0_662:
	v_readlane_b32 s4, v255, 10
	s_add_i32 s89, s89, s4
	s_max_i32 s4, s89, 4
	s_add_i32 s4, s4, -4
	s_min_u32 s4, s4, 56
	ds_read_b64_tr_b16 v[132:133], v216 offset:40960
	ds_read_b64_tr_b16 v[134:135], v216 offset:41472
	s_waitcnt lgkmcnt(9)
	v_mfma_f32_32x32x16_bf16 v[112:127], v[180:183], v[176:179], v[64:79]
	v_add_f32_e32 v0, v96, v97
	v_cvt_pk_bf16_f32 v160, v96, v97
	v_add_f32_e32 v0, v98, v0
	v_cvt_pk_bf16_f32 v161, v98, v99
	v_add_f32_e32 v0, v99, v0
	v_add_f32_e32 v0, v100, v0
	v_add_f32_e32 v0, v101, v0
	ds_read_b64_tr_b16 v[128:129], v216 offset:45056
	ds_read_b64_tr_b16 v[130:131], v216 offset:45568
	s_waitcnt lgkmcnt(10)
	v_mfma_f32_32x32x16_bf16 v[64:79], v[156:159], v[176:179], v[64:79]
	v_add_f32_e32 v0, v102, v0
	v_cvt_pk_bf16_f32 v162, v100, v101
	v_add_f32_e32 v0, v103, v0
	v_cvt_pk_bf16_f32 v163, v102, v103
	v_add_f32_e32 v0, v104, v0
	v_add_f32_e32 v0, v105, v0
	ds_read_b64_tr_b16 v[136:137], v216 offset:41984
	ds_read_b64_tr_b16 v[138:139], v216 offset:42496
	s_waitcnt lgkmcnt(11)
	v_mfma_f32_32x32x16_bf16 v[112:127], v[152:155], v[172:175], v[112:127]
	v_add_f32_e32 v0, v106, v0
	v_cvt_pk_bf16_f32 v10, v104, v105
	v_add_f32_e32 v0, v107, v0
	v_cvt_pk_bf16_f32 v11, v106, v107
	v_add_f32_e32 v0, v108, v0
	v_add_f32_e32 v0, v109, v0
	ds_read_b64_tr_b16 v[140:141], v216 offset:46080
	ds_read_b64_tr_b16 v[142:143], v216 offset:46592
	s_waitcnt lgkmcnt(12)
	v_mfma_f32_32x32x16_bf16 v[64:79], v[148:151], v[172:175], v[64:79]
	v_add_f32_e32 v0, v110, v0
	v_cvt_pk_bf16_f32 v12, v108, v109
	v_add_f32_e32 v0, v111, v0
	v_cvt_pk_bf16_f32 v13, v110, v111
	v_add_f32_e32 v0, v80, v0
	v_add_f32_e32 v0, v81, v0
	ds_read_b64_tr_b16 v[148:149], v216 offset:43008
	ds_read_b64_tr_b16 v[150:151], v216 offset:43520
	s_waitcnt lgkmcnt(13)
	v_mfma_f32_32x32x16_bf16 v[112:127], v[144:147], v[168:171], v[112:127]
	v_add_f32_e32 v0, v82, v0
	v_cvt_pk_bf16_f32 v6, v80, v81
	v_add_f32_e32 v0, v83, v0
	v_cvt_pk_bf16_f32 v7, v82, v83
	v_add_f32_e32 v0, v84, v0
	v_add_f32_e32 v0, v85, v0
	ds_read_b64_tr_b16 v[144:145], v216 offset:47104
	ds_read_b64_tr_b16 v[146:147], v216 offset:47616
	s_waitcnt lgkmcnt(14)
	v_mfma_f32_32x32x16_bf16 v[64:79], v[26:29], v[168:171], v[64:79]
	v_add_f32_e32 v0, v86, v0
	v_cvt_pk_bf16_f32 v8, v84, v85
	v_add_f32_e32 v0, v87, v0
	v_cvt_pk_bf16_f32 v9, v86, v87
	v_add_f32_e32 v0, v88, v0
	v_add_f32_e32 v0, v89, v0
	ds_read_b64_tr_b16 v[152:153], v216 offset:44032
	ds_read_b64_tr_b16 v[154:155], v216 offset:44544
	s_waitcnt lgkmcnt(14)
	v_mfma_f32_32x32x16_bf16 v[112:127], v[22:25], v[164:167], v[112:127]
	v_add_f32_e32 v0, v90, v0
	v_cvt_pk_bf16_f32 v2, v88, v89
	v_add_f32_e32 v0, v91, v0
	v_cvt_pk_bf16_f32 v3, v90, v91
	v_add_f32_e32 v0, v92, v0
	v_add_f32_e32 v0, v93, v0
	ds_read_b64_tr_b16 v[156:157], v216 offset:48128
	ds_read_b64_tr_b16 v[158:159], v216 offset:48640
	v_mfma_f32_32x32x16_bf16 v[64:79], v[18:21], v[164:167], v[64:79]
	v_add_f32_e32 v0, v94, v0
	v_cvt_pk_bf16_f32 v4, v92, v93
	v_add_f32_e32 v0, v95, v0
	v_cvt_pk_bf16_f32 v5, v94, v95
	v_add_f32_e32 v0, 0, v0
	v_readlane_b32 s5, v255, 11
	s_add_i32 s5, s5, 11
	s_sub_i32 s4, s5, s4
	s_cmp_gt_u32 s4, 7
	s_cbranch_scc1 .LBB0_728
	s_sub_i32 s4, s5, s89
	s_mulk_i32 s4, 0x7c
	s_add_i32 s4, s4, 0
	v_lshlrev_b32_e32 v14, 2, v214
	v_sub_u32_e32 v14, s4, v14
	v_add_u32_e32 v15, 0x16000, v14
	v_lshl_add_u32 v17, v217, 2, v15
	v_mov_b32_e32 v15, 0
	s_and_saveexec_b64 s[4:5], s[12:13]
	v_readlane_b32 s90, v255, 15
	v_readlane_b32 s92, v254, 58
	s_movk_i32 s82, 0x1000
	v_readlane_b32 s33, v255, 12
	v_readlane_b32 s91, v255, 16
	ds_read_b32 v15, v17 offset:928
	s_or_b64 exec, exec, s[4:5]
	ds_read_b32 v14, v17 offset:1056
	v_mov_b32_e32 v19, 0
	s_and_saveexec_b64 s[4:5], s[16:17]
	v_readlane_b32 s88, v255, 17
	v_readlane_b32 s89, v255, 18
	ds_read_b32 v19, v17 offset:932
	s_or_b64 exec, exec, s[4:5]
	ds_read_b32 v18, v17 offset:1060
	ds_read_b32 v21, v17 offset:936
	ds_read_b32 v20, v17 offset:1064
	ds_read_b32 v23, v17 offset:940
	ds_read_b32 v22, v17 offset:1068
	ds_read_b32 v25, v17 offset:960
	ds_read_b32 v24, v17 offset:1088
	ds_read_b32 v27, v17 offset:964
	ds_read_b32 v26, v17 offset:1092
	ds_read_b32 v29, v17 offset:968
	ds_read_b32 v28, v17 offset:1096
	ds_read_b32 v31, v17 offset:972
	ds_read_b32 v30, v17 offset:1100
	ds_read_b32 v88, v17 offset:992
	ds_read_b32 v89, v17 offset:1120
	ds_read_b32 v91, v17 offset:996
	ds_read_b32 v90, v17 offset:1124
	ds_read_b32 v93, v17 offset:1000
	ds_read_b32 v92, v17 offset:1128
	ds_read_b32 v95, v17 offset:1004
	ds_read_b32 v94, v17 offset:1132
	ds_read_b32 v97, v17 offset:1024
	ds_read_b32 v96, v17 offset:1152
	ds_read_b32 v99, v17 offset:1028
	ds_read_b32 v98, v17 offset:1156
	ds_read_b32 v101, v17 offset:1032
	ds_read_b32 v100, v17 offset:1160
	ds_read_b32 v103, v17 offset:1036
	ds_read_b32 v102, v17 offset:1164
	s_waitcnt lgkmcnt(0)
	v_add_f32_e32 v14, v64, v14
	v_cndmask_b32_e64 v64, v16, v14, s[14:15]
	v_add_f32_e32 v14, v113, v19
	v_cndmask_b32_e64 v81, v16, v14, s[16:17]
	v_add_f32_e32 v14, v65, v18
	v_cndmask_b32_e64 v65, v16, v14, s[18:19]
	v_add_f32_e32 v14, v114, v21
	v_cndmask_b32_e64 v82, v16, v14, s[20:21]
	v_add_f32_e32 v14, v66, v20
	v_cndmask_b32_e64 v66, v16, v14, s[22:23]
	v_add_f32_e32 v14, v115, v23
	v_cndmask_b32_e64 v83, v16, v14, s[24:25]
	v_add_f32_e32 v14, v67, v22
	v_cndmask_b32_e64 v67, v16, v14, s[26:27]
	v_add_f32_e32 v14, v116, v25
	v_cndmask_b32_e64 v84, v16, v14, s[28:29]
	v_add_f32_e32 v14, v68, v24
	v_cndmask_b32_e64 v68, v16, v14, s[30:31]
	v_add_f32_e32 v14, v117, v27
	v_cndmask_b32_e64 v85, v16, v14, s[34:35]
	v_add_f32_e32 v14, v69, v26
	v_cndmask_b32_e64 v69, v16, v14, s[36:37]
	v_add_f32_e32 v14, v118, v29
	v_cndmask_b32_e64 v86, v16, v14, s[38:39]
	v_add_f32_e32 v14, v70, v28
	v_cndmask_b32_e64 v70, v16, v14, s[40:41]
	v_add_f32_e32 v14, v119, v31
	v_cndmask_b32_e64 v87, v16, v14, s[42:43]
	v_add_f32_e32 v14, v71, v30
	v_cndmask_b32_e64 v71, v16, v14, s[44:45]
	v_add_f32_e32 v14, v120, v88
	v_cndmask_b32_e64 v88, v16, v14, s[46:47]
	v_add_f32_e32 v14, v72, v89
	v_cndmask_b32_e64 v72, v16, v14, s[48:49]
	v_add_f32_e32 v14, v121, v91
	v_cndmask_b32_e64 v89, v16, v14, s[50:51]
	v_add_f32_e32 v14, v73, v90
	v_cndmask_b32_e64 v73, v16, v14, s[52:53]
	v_add_f32_e32 v14, v122, v93
	v_cndmask_b32_e64 v90, v16, v14, s[54:55]
	v_add_f32_e32 v14, v74, v92
	v_cndmask_b32_e64 v74, v16, v14, s[56:57]
	v_add_f32_e32 v14, v123, v95
	v_cndmask_b32_e64 v91, v16, v14, s[58:59]
	v_add_f32_e32 v14, v75, v94
	v_cndmask_b32_e64 v75, v16, v14, s[60:61]
	v_add_f32_e32 v14, v124, v97
	v_cndmask_b32_e64 v92, v16, v14, s[62:63]
	v_add_f32_e32 v14, v76, v96
	v_cndmask_b32_e64 v76, v16, v14, s[64:65]
	v_add_f32_e32 v14, v125, v99
	v_cndmask_b32_e64 v93, v16, v14, s[66:67]
	v_add_f32_e32 v14, v77, v98
	v_cndmask_b32_e64 v77, v16, v14, s[68:69]
	v_add_f32_e32 v14, v126, v101
	v_cndmask_b32_e64 v94, v16, v14, s[70:71]
	v_add_f32_e32 v14, v78, v100
	v_cndmask_b32_e64 v78, v16, v14, s[72:73]
	v_add_f32_e32 v14, v127, v103
	v_add_f32_e32 v15, v112, v15
	v_cndmask_b32_e64 v95, v16, v14, s[74:75]
	v_add_f32_e32 v14, v79, v102
	v_cndmask_b32_e64 v80, v16, v15, s[12:13]
	v_cndmask_b32_e64 v79, v16, v14, s[76:77]
	s_branch .LBB0_729
